# post-mix: all nine loads of a row issued together, 16-lane sums by DPP instead of LDS bpermute
# speedup vs baseline: 1.0091x; 1.0091x over previous
; __device__ __forceinline__ void phase_postmix(const Params& p, int l, int nrows) {
;     ...
;   for (int r = blockIdx.x * 4 + (tidq >> 6); r < nrows; r += gridDim.x * 4) {
;     bf16_t* pr = P + (size_t)r * PC;
;     const size_t so = (size_t)r * 256 + c0;
;     const size_t st = (size_t)NTOK * 256;
;     {
;       const u32x2 a = *(const u32x2*)(SC + so), bq = *(const u32x2*)(SC + st + so);
;       const float o0 = bflo(a.x) + bflo(bq.x), o1 = bfhi(a.x) + bfhi(bq.x), o2 = bflo(a.y) + bflo(bq.y), o3 = bfhi(a.y) + bfhi(bq.y);
;       const float ss = sum16(o0 * o0 + o1 * o1 + o2 * o2 + o3 * o3);
;       const float rstd = rsqrtf(ss * (1.f / 64.f) + 1e-6f);
;       const u32x2 z = *(const u32x2*)(pr + C_DNZ + c0);
;       u32x2 o;
;       o.x = pack2(o0 * rstd * gdn.x * silu(bflo(z.x)), o1 * rstd * gdn.y * silu(bfhi(z.x)));
;       o.y = pack2(o2 * rstd * gdn.z * silu(bflo(z.y)), o3 * rstd * gdn.w * silu(bfhi(z.y)));
;       *(u32x2*)(pr + C_YDN + c0) = o;
;     }
;     {
;       const u32x2 a = *(const u32x2*)(SC + 2 * st + so), bq = *(const u32x2*)(SC + 3 * st + so);
;       const float o0 = bflo(a.x) + bflo(bq.x), o1 = bfhi(a.x) + bfhi(bq.x), o2 = bflo(a.y) + bflo(bq.y), o3 = bfhi(a.y) + bfhi(bq.y);
;       const float ss = sum16(o0 * o0 + o1 * o1 + o2 * o2 + o3 * o3);
;       const float rstd = rsqrtf(ss * (1.f / 64.f) + 1e-6f);
;       const u32x2 z = *(const u32x2*)(pr + C_HGG + c0);
;       u32x2 o;
;       o.x = pack2(o0 * rstd * ghg.x * sigm(bflo(z.x)), o1 * rstd * ghg.y * sigm(bfhi(z.x)));
;       o.y = pack2(o2 * rstd * ghg.z * sigm(bflo(z.y)), o3 * rstd * ghg.w * sigm(bfhi(z.y)));
;       *(u32x2*)(pr + C_YHG + c0) = o;
;     }
;     {
;       const u32x2 a = *(const u32x2*)(SC + 4 * st + so), bq = *(const u32x2*)(SC + 5 * st + so);
;       const u32x2 u = *(const u32x2*)(pr + C_S5U + c0);
;       float y[4];
;       y[0] = bflo(a.x) + bflo(bq.x) + dsk.x * bflo(u.x);
;       y[1] = bfhi(a.x) + bfhi(bq.x) + dsk.y * bfhi(u.x);
;       y[2] = bflo(a.y) + bflo(bq.y) + dsk.z * bflo(u.y);
;       y[3] = bfhi(a.y) + bfhi(bq.y) + dsk.w * bfhi(u.y);
; #pragma unroll
;       for (int e = 0; e < 4; ++e) {
;         const float x = y[e];
;         const float uu = 0.7978845608028654f * (x + 0.044715f * x * x * x);
;         const float th = 1.f - 2.f / (1.f + __expf(2.f * uu));
;         y[e] = 0.5f * x * (1.f + th);
;       }
.LBB0_97:
	v_ashrrev_i32_e32 v15, 31, v14
	v_lshlrev_b64 v[18:19], 9, v[14:15]
	v_or_b32_e32 v18, v18, v0
	v_mad_i64_i32 v[16:17], s[46:47], v14, s74, v[94:95]
	v_lshl_add_u64 v[20:21], v[104:105], 0, v[18:19]
	v_lshl_add_u64 v[26:27], v[108:109], 0, v[18:19]
	global_load_dwordx2 v[20:21], v[20:21], off
	v_lshl_add_u64 v[16:17], v[16:17], 0, v[0:1]
	global_load_dwordx2 v[26:27], v[26:27], off
	v_add_u32_e32 v14, s38, v14
	global_load_dwordx2 v[28:29], v[16:17], off offset:1536
	v_lshl_add_u64 v[196:197], v[110:111], 0, v[18:19]
	global_load_dwordx2 v[200:201], v[196:197], off
	v_lshl_add_u64 v[196:197], v[112:113], 0, v[18:19]
	global_load_dwordx2 v[202:203], v[196:197], off
	v_add_co_u32_e32 v196, vcc, s76, v16
	s_nop 1
	v_addc_co_u32_e32 v197, vcc, 0, v17, vcc
	global_load_dwordx2 v[204:205], v[196:197], off offset:544
	v_lshl_add_u64 v[196:197], v[114:115], 0, v[18:19]
	global_load_dwordx2 v[206:207], v[196:197], off
	v_lshl_add_u64 v[196:197], v[116:117], 0, v[18:19]
	global_load_dwordx2 v[208:209], v[196:197], off
	global_load_dwordx2 v[210:211], v[16:17], off offset:2080
	s_waitcnt vmcnt(8)
	v_lshlrev_b32_e32 v30, 16, v21
	v_and_b32_e32 v31, 0xffff0000, v21
	v_lshlrev_b32_e32 v34, 16, v20
	v_and_b32_e32 v35, 0xffff0000, v20
	s_waitcnt vmcnt(7)
	v_lshlrev_b32_e32 v20, 16, v26
	v_and_b32_e32 v21, 0xffff0000, v26
	v_pk_add_f32 v[20:21], v[34:35], v[20:21]
	s_waitcnt vmcnt(6)
	v_lshlrev_b32_e32 v34, 16, v28
	v_mul_f32_e32 v15, 0xbfb8aa3b, v34
	v_exp_f32_e32 v15, v15
	v_and_b32_e32 v35, 0xffff0000, v28
	v_lshlrev_b32_e32 v32, 16, v27
	v_and_b32_e32 v33, 0xffff0000, v27
	v_add_f32_e32 v15, 1.0, v15
	v_rcp_f32_e32 v36, v15
	v_mul_f32_e32 v15, 0xbfb8aa3b, v35
	v_exp_f32_e32 v15, v15
	v_pk_add_f32 v[30:31], v[30:31], v[32:33]
	v_pk_mul_f32 v[26:27], v[20:21], v[20:21]
	v_pk_mul_f32 v[32:33], v[30:31], v[30:31]
	v_add_f32_e32 v15, 1.0, v15
	v_rcp_f32_e32 v37, v15
	v_add_f32_e32 v15, v26, v27
	v_add_f32_e32 v15, v32, v15
	v_add_f32_e32 v15, v33, v15
	v_lshlrev_b32_e32 v28, 16, v29
	v_and_b32_e32 v29, 0xffff0000, v29
	v_pk_mul_f32 v[34:35], v[36:37], v[34:35]
	v_add_f32_dpp v15, v15, v15 quad_perm:[1,0,3,2] row_mask:0xf bank_mask:0xf
	s_nop 1
	v_add_f32_dpp v15, v15, v15 quad_perm:[2,3,0,1] row_mask:0xf bank_mask:0xf
	s_nop 1
	v_add_f32_dpp v15, v15, v15 row_half_mirror row_mask:0xf bank_mask:0xf
	s_nop 1
	v_add_f32_dpp v15, v15, v15 row_mirror row_mask:0xf bank_mask:0xf
	v_fmamk_f32 v15, v15, 0x3c800000, v174
	v_cmp_gt_f32_e32 vcc, s88, v15
	v_mul_f32_e32 v26, 0x4b800000, v15
	s_nop 0
	v_cndmask_b32_e32 v15, v15, v26, vcc
	v_rsq_f32_e32 v15, v15
	s_nop 0
	v_mul_f32_e32 v26, 0x45800000, v15
	v_cndmask_b32_e32 v26, v15, v26, vcc
	v_mul_f32_e32 v15, 0xbfb8aa3b, v28
	v_exp_f32_e32 v15, v15
	v_pk_mul_f32 v[20:21], v[20:21], v[26:27] op_sel_hi:[1,0]
	v_pk_mul_f32 v[26:27], v[30:31], v[26:27] op_sel_hi:[1,0]
	v_pk_mul_f32 v[20:21], v[2:3], v[20:21]
	v_add_f32_e32 v15, 1.0, v15
	v_rcp_f32_e32 v32, v15
	v_mul_f32_e32 v15, 0xbfb8aa3b, v29
	v_exp_f32_e32 v15, v15
	v_pk_mul_f32 v[26:27], v[4:5], v[26:27]
	v_pk_mul_f32 v[20:21], v[34:35], v[20:21]
	v_add_f32_e32 v15, 1.0, v15
	v_rcp_f32_e32 v33, v15
	v_cvt_pk_bf16_f32 v20, v20, v21
	v_pk_mul_f32 v[28:29], v[32:33], v[28:29]
	s_nop 0
	v_pk_mul_f32 v[26:27], v[28:29], v[26:27]
	v_cvt_pk_bf16_f32 v21, v26, v27
	global_store_dwordx2 v[16:17], v[20:21], off
	s_nop 0
	s_nop 0
	s_waitcnt vmcnt(6)
	v_mov_b32_e32 v20, v200
	v_mov_b32_e32 v21, v201
	v_lshlrev_b32_e32 v32, 16, v21
	v_and_b32_e32 v33, 0xffff0000, v21
	v_lshlrev_b32_e32 v36, 16, v20
	v_and_b32_e32 v37, 0xffff0000, v20
	s_waitcnt vmcnt(4)
	v_mov_b32_e32 v26, v202
	v_mov_b32_e32 v27, v203
	v_mov_b32_e32 v28, v204
	v_mov_b32_e32 v29, v205
	v_lshlrev_b32_e32 v15, 16, v28
	v_mul_f32_e32 v15, 0xbfb8aa3b, v15
	v_exp_f32_e32 v15, v15
	v_lshlrev_b32_e32 v20, 16, v26
	v_and_b32_e32 v21, 0xffff0000, v26
	v_lshlrev_b32_e32 v34, 16, v27
	v_add_f32_e32 v15, 1.0, v15
	v_rcp_f32_e32 v30, v15
	v_and_b32_e32 v15, 0xffff0000, v28
	v_mul_f32_e32 v15, 0xbfb8aa3b, v15
	v_exp_f32_e32 v15, v15
	v_and_b32_e32 v35, 0xffff0000, v27
	v_pk_add_f32 v[20:21], v[36:37], v[20:21]
	v_pk_add_f32 v[32:33], v[32:33], v[34:35]
	v_add_f32_e32 v15, 1.0, v15
	v_rcp_f32_e32 v31, v15
	v_lshlrev_b32_e32 v15, 16, v29
	v_mul_f32_e32 v15, 0xbfb8aa3b, v15
	v_exp_f32_e32 v15, v15
	v_pk_mul_f32 v[26:27], v[20:21], v[20:21]
	v_pk_mul_f32 v[34:35], v[32:33], v[32:33]
	v_add_f32_e32 v15, 1.0, v15
	v_rcp_f32_e32 v28, v15
	v_and_b32_e32 v15, 0xffff0000, v29
	v_mul_f32_e32 v15, 0xbfb8aa3b, v15
	v_exp_f32_e32 v15, v15
	s_nop 0
	v_add_f32_e32 v15, 1.0, v15
	v_rcp_f32_e32 v29, v15
	v_add_f32_e32 v15, v26, v27
	v_add_f32_e32 v15, v34, v15
	v_add_f32_e32 v15, v35, v15
	s_nop 1
	v_add_f32_dpp v15, v15, v15 quad_perm:[1,0,3,2] row_mask:0xf bank_mask:0xf
	s_nop 1
	v_add_f32_dpp v15, v15, v15 quad_perm:[2,3,0,1] row_mask:0xf bank_mask:0xf
	s_nop 1
	v_add_f32_dpp v15, v15, v15 row_half_mirror row_mask:0xf bank_mask:0xf
	s_nop 1
	v_add_f32_dpp v15, v15, v15 row_mirror row_mask:0xf bank_mask:0xf
	v_fmamk_f32 v15, v15, 0x3c800000, v174
	v_cmp_gt_f32_e32 vcc, s88, v15
	v_mul_f32_e32 v26, 0x4b800000, v15
	s_nop 0
	v_cndmask_b32_e32 v15, v15, v26, vcc
	v_rsq_f32_e32 v15, v15
	s_nop 0
	v_mul_f32_e32 v26, 0x45800000, v15
	v_cndmask_b32_e32 v26, v15, v26, vcc
	v_pk_mul_f32 v[20:21], v[20:21], v[26:27] op_sel_hi:[1,0]
	v_pk_mul_f32 v[26:27], v[32:33], v[26:27] op_sel_hi:[1,0]
	v_pk_mul_f32 v[20:21], v[6:7], v[20:21]
	v_pk_mul_f32 v[26:27], v[8:9], v[26:27]
	v_pk_mul_f32 v[20:21], v[30:31], v[20:21]
	v_pk_mul_f32 v[26:27], v[28:29], v[26:27]
	v_cvt_pk_bf16_f32 v20, v20, v21
	v_cvt_pk_bf16_f32 v21, v26, v27
	global_store_dwordx2 v[16:17], v[20:21], off offset:2592
	s_nop 0
	s_waitcnt vmcnt(4)
; __device__ __forceinline__ float bflo(unsigned u) { return __uint_as_float(u << 16); }
; __device__ __forceinline__ float bfhi(unsigned u) { return __uint_as_float(u & 0xffff0000u); }
; __device__ __forceinline__ void phase_postmix(const Params& p, int l, int nrows) {
;     ...
;     {
;       const u32x2 a = *(const u32x2*)(SC + 4 * st + so), bq = *(const u32x2*)(SC + 5 * st + so);
;       const u32x2 u = *(const u32x2*)(pr + C_S5U + c0);
;       float y[4];
;       y[0] = bflo(a.x) + bflo(bq.x) + dsk.x * bflo(u.x);
;       y[1] = bfhi(a.x) + bfhi(bq.x) + dsk.y * bfhi(u.x);
;       y[2] = bflo(a.y) + bflo(bq.y) + dsk.z * bflo(u.y);
;       y[3] = bfhi(a.y) + bfhi(bq.y) + dsk.w * bfhi(u.y);
; #pragma unroll
;       for (int e = 0; e < 4; ++e) {
;         const float x = y[e];
;         const float uu = 0.7978845608028654f * (x + 0.044715f * x * x * x);
;         const float th = 1.f - 2.f / (1.f + __expf(2.f * uu));
;         y[e] = 0.5f * x * (1.f + th);
;       }
;       u32x2 o; o.x = pack2(y[0], y[1]); o.y = pack2(y[2], y[3]);
;       *(u32x2*)(pr + C_S5G + c0) = o;
;     }
	v_mov_b32_e32 v20, v206
	v_mov_b32_e32 v21, v207
	v_lshlrev_b32_e32 v28, 16, v20
	v_and_b32_e32 v29, 0xffff0000, v20
	s_waitcnt vmcnt(3)
	v_mov_b32_e32 v18, v208
	v_mov_b32_e32 v19, v209
	v_lshlrev_b32_e32 v30, 16, v18
	v_and_b32_e32 v31, 0xffff0000, v18
	v_pk_add_f32 v[28:29], v[28:29], v[30:31]
	s_waitcnt vmcnt(2)
	v_mov_b32_e32 v26, v210
	v_mov_b32_e32 v27, v211
	v_lshlrev_b32_e32 v30, 16, v26
	v_and_b32_e32 v31, 0xffff0000, v26
	v_pk_fma_f32 v[28:29], v[10:11], v[30:31], v[28:29]
	s_nop 0
	v_mul_f32_e32 v15, 0x3d372713, v28
	v_mul_f32_e32 v15, v28, v15
	v_fma_f32 v15, v28, v15, v28
	v_mul_f32_e32 v15, 0x3f4c422a, v15
	v_add_f32_e32 v15, v15, v15
	v_mul_f32_e32 v15, 0x3fb8aa3b, v15
	v_exp_f32_e32 v30, v15
	v_mul_f32_e32 v15, 0x3d372713, v29
	v_mul_f32_e32 v15, v29, v15
	v_fma_f32 v15, v29, v15, v29
	v_mul_f32_e32 v15, 0x3f4c422a, v15
	v_add_f32_e32 v15, v15, v15
	v_mul_f32_e32 v15, 0x3fb8aa3b, v15
	v_exp_f32_e32 v31, v15
	v_pk_mul_f32 v[28:29], v[28:29], 0.5 op_sel_hi:[1,0]
	v_pk_add_f32 v[30:31], v[30:31], 1.0 op_sel_hi:[1,0]
	s_nop 0
	v_div_scale_f32 v15, s[46:47], v31, v31, 2.0
	v_rcp_f32_e32 v18, v15
	s_nop 0
	v_fma_f32 v20, -v15, v18, 1.0
	v_fmac_f32_e32 v18, v20, v18
	v_div_scale_f32 v20, vcc, 2.0, v31, 2.0
	v_mul_f32_e32 v26, v20, v18
	v_fma_f32 v32, -v15, v26, v20
	v_fmac_f32_e32 v26, v32, v18
	v_fma_f32 v15, -v15, v26, v20
	v_div_fmas_f32 v15, v15, v18, v26
	v_div_fixup_f32 v31, v15, v31, 2.0
	v_div_scale_f32 v15, s[46:47], v30, v30, 2.0
	v_rcp_f32_e32 v18, v15
	s_nop 0
	v_fma_f32 v20, -v15, v18, 1.0
	v_fmac_f32_e32 v18, v20, v18
	v_div_scale_f32 v20, vcc, 2.0, v30, 2.0
	v_mul_f32_e32 v26, v20, v18
	v_fma_f32 v32, -v15, v26, v20
	v_fmac_f32_e32 v26, v32, v18
	v_fma_f32 v15, -v15, v26, v20
	v_div_fmas_f32 v15, v15, v18, v26
	v_lshlrev_b32_e32 v20, 16, v21
	v_and_b32_e32 v21, 0xffff0000, v21
	v_lshlrev_b32_e32 v18, 16, v19
	v_and_b32_e32 v19, 0xffff0000, v19
	v_pk_add_f32 v[18:19], v[20:21], v[18:19]
	v_lshlrev_b32_e32 v20, 16, v27
	v_and_b32_e32 v21, 0xffff0000, v27
	v_pk_fma_f32 v[18:19], v[12:13], v[20:21], v[18:19]
	v_div_fixup_f32 v30, v15, v30, 2.0
	v_mul_f32_e32 v15, 0x3d372713, v18
	v_mul_f32_e32 v15, v18, v15
	v_fma_f32 v15, v18, v15, v18
	v_mul_f32_e32 v15, 0x3f4c422a, v15
	v_add_f32_e32 v15, v15, v15
	v_mul_f32_e32 v15, 0x3fb8aa3b, v15
	v_exp_f32_e32 v20, v15
	v_mul_f32_e32 v15, 0x3d372713, v19
	v_mul_f32_e32 v15, v19, v15
	v_fma_f32 v15, v19, v15, v19
	v_mul_f32_e32 v15, 0x3f4c422a, v15
	v_add_f32_e32 v15, v15, v15
	v_mul_f32_e32 v15, 0x3fb8aa3b, v15
	v_exp_f32_e32 v21, v15
	v_pk_add_f32 v[30:31], v[30:31], 1.0 op_sel_hi:[1,0] neg_lo:[1,0] neg_hi:[1,0]
	v_pk_mul_f32 v[18:19], v[18:19], 0.5 op_sel_hi:[1,0]
	v_pk_add_f32 v[30:31], v[30:31], 1.0 op_sel_hi:[1,0]
	v_pk_add_f32 v[20:21], v[20:21], 1.0 op_sel_hi:[1,0]
	v_pk_mul_f32 v[28:29], v[28:29], v[30:31]
	v_div_scale_f32 v15, s[46:47], v21, v21, 2.0
	v_rcp_f32_e32 v26, v15
	s_nop 0
	v_fma_f32 v27, -v15, v26, 1.0
	v_fmac_f32_e32 v26, v27, v26
	v_div_scale_f32 v27, vcc, 2.0, v21, 2.0
	v_mul_f32_e32 v30, v27, v26
	v_fma_f32 v31, -v15, v30, v27
	v_fmac_f32_e32 v30, v31, v26
	v_fma_f32 v15, -v15, v30, v27
	v_div_fmas_f32 v15, v15, v26, v30
	v_div_fixup_f32 v21, v15, v21, 2.0
	v_div_scale_f32 v15, s[46:47], v20, v20, 2.0
	v_rcp_f32_e32 v26, v15
	s_nop 0
	v_fma_f32 v27, -v15, v26, 1.0
	v_fmac_f32_e32 v26, v27, v26
	v_div_scale_f32 v27, vcc, 2.0, v20, 2.0
	v_mul_f32_e32 v30, v27, v26
	v_fma_f32 v31, -v15, v30, v27
	v_fmac_f32_e32 v30, v31, v26
	v_fma_f32 v15, -v15, v30, v27
	v_div_fmas_f32 v15, v15, v26, v30
	v_div_fixup_f32 v20, v15, v20, 2.0
	v_pk_add_f32 v[20:21], v[20:21], 1.0 op_sel_hi:[1,0] neg_lo:[1,0] neg_hi:[1,0]
	v_cmp_le_i32_e32 vcc, s22, v14
	v_pk_add_f32 v[20:21], v[20:21], 1.0 op_sel_hi:[1,0]
	s_or_b64 s[42:43], vcc, s[42:43]
	v_pk_mul_f32 v[18:19], v[18:19], v[20:21]
	v_cvt_pk_bf16_f32 v20, v28, v29
	v_cvt_pk_bf16_f32 v21, v18, v19
	global_store_dwordx2 v[16:17], v[20:21], off offset:512
	s_andn2_b64 exec, exec, s[42:43]
	s_cbranch_execnz .LBB0_97
